# attention output rows through a per-wave LDS scratch: whole 128-byte lines per store
# baseline (speedup 1.0000x reference)
.Lm_nox_13:
	global_load_dwordx4 v[4:7], v164, s[38:39] offset:0
	global_load_dwordx4 v[8:11], v164, s[38:39] offset:512
	global_load_dwordx4 v[12:15], v164, s[38:39] offset:1024
	global_load_dwordx4 v[16:19], v164, s[38:39] offset:1536
	global_load_dwordx4 v[20:23], v164, s[38:39] offset:2048
	global_load_dwordx4 v[24:27], v164, s[38:39] offset:2560
	global_load_dwordx4 v[28:31], v164, s[38:39] offset:3072
	global_load_dwordx4 v[32:35], v164, s[38:39] offset:3584
	global_load_dwordx4 v[36:39], v168, s[40:41]
	global_load_dwordx4 v[40:43], v169, s[40:41]
	s_add_u32 s38, s38, s46
	s_addc_u32 s39, s39, s55
	s_add_u32 s40, s40, s47
	s_addc_u32 s41, s41, s55
	s_waitcnt lgkmcnt(0)
	s_barrier

.Lm_nox_24:
	global_load_dwordx4 v[44:47], v164, s[38:39] offset:0
	global_load_dwordx4 v[48:51], v164, s[38:39] offset:512
	global_load_dwordx4 v[52:55], v164, s[38:39] offset:1024
	global_load_dwordx4 v[56:59], v164, s[38:39] offset:1536
	global_load_dwordx4 v[60:63], v164, s[38:39] offset:2048
	global_load_dwordx4 v[64:67], v164, s[38:39] offset:2560
	global_load_dwordx4 v[68:71], v164, s[38:39] offset:3072
	global_load_dwordx4 v[72:75], v164, s[38:39] offset:3584
	global_load_dwordx4 v[76:79], v168, s[40:41]
	global_load_dwordx4 v[80:83], v169, s[40:41]
	s_add_u32 s38, s38, s46
	s_addc_u32 s39, s39, s55
	s_add_u32 s40, s40, s47
	s_addc_u32 s41, s41, s55

.Lm_hi_25:
	v_add_u32_e32 v2, s14, v173
	ds_read_b32 v1, v2
	ds_read_b64_tr_b16 v[116:117], v198 offset:0
	ds_read_b64_tr_b16 v[118:119], v198 offset:1088
	ds_read_b64_tr_b16 v[120:121], v192 offset:43008
	ds_read_b64_tr_b16 v[122:123], v192 offset:43264
	ds_read_b64_tr_b16 v[124:125], v198 offset:4352
	ds_read_b64_tr_b16 v[126:127], v198 offset:5440
	ds_read_b64_tr_b16 v[128:129], v192 offset:44032
	ds_read_b64_tr_b16 v[130:131], v192 offset:44288
	ds_read_b64_tr_b16 v[132:133], v198 offset:8704
	ds_read_b64_tr_b16 v[134:135], v198 offset:9792
	ds_read_b64_tr_b16 v[136:137], v192 offset:45056
	ds_read_b64_tr_b16 v[138:139], v192 offset:45312
	s_waitcnt lgkmcnt(12)
	v_exp_f32_e32 v1, v1
	s_nop 0
	v_mul_f32_e32 v176, v176, v1
	v_mul_f32_e32 v177, v177, v1
	v_mul_f32_e32 v178, v178, v1
	v_mul_f32_e32 v179, v179, v1
	v_mul_f32_e32 v180, v180, v1
	v_mul_f32_e32 v181, v181, v1
	v_mul_f32_e32 v182, v182, v1
	v_mul_f32_e32 v183, v183, v1
	v_mul_f32_e32 v184, v184, v1
	v_mul_f32_e32 v185, v185, v1
	v_mul_f32_e32 v186, v186, v1
	v_mul_f32_e32 v187, v187, v1
	v_mul_f32_e32 v188, v188, v1
	v_mul_f32_e32 v189, v189, v1
	v_mul_f32_e32 v190, v190, v1
	v_mul_f32_e32 v191, v191, v1
	s_nop 1
	s_waitcnt lgkmcnt(8)
	v_mfma_f32_32x32x16_bf16 v[176:191], v[116:119], v[120:123], v[176:191]
	ds_read_b64_tr_b16 v[116:117], v198 offset:13056
	ds_read_b64_tr_b16 v[118:119], v198 offset:14144
	ds_read_b64_tr_b16 v[120:121], v192 offset:46080
	ds_read_b64_tr_b16 v[122:123], v192 offset:46336
	s_waitcnt lgkmcnt(8)
	v_mfma_f32_32x32x16_bf16 v[176:191], v[124:127], v[128:131], v[176:191]
	ds_read_b64_tr_b16 v[124:125], v198 offset:17408
	ds_read_b64_tr_b16 v[126:127], v198 offset:18496
	ds_read_b64_tr_b16 v[128:129], v192 offset:47104
	ds_read_b64_tr_b16 v[130:131], v192 offset:47360
	s_waitcnt lgkmcnt(8)
	v_mfma_f32_32x32x16_bf16 v[176:191], v[132:135], v[136:139], v[176:191]
	ds_read_b64_tr_b16 v[132:133], v198 offset:21760
	ds_read_b64_tr_b16 v[134:135], v198 offset:22848
	ds_read_b64_tr_b16 v[136:137], v192 offset:48128
	ds_read_b64_tr_b16 v[138:139], v192 offset:48384
	s_waitcnt lgkmcnt(8)
	v_mfma_f32_32x32x16_bf16 v[176:191], v[116:119], v[120:123], v[176:191]
	ds_read_b64_tr_b16 v[116:117], v198 offset:26112
	ds_read_b64_tr_b16 v[118:119], v198 offset:27200
	ds_read_b64_tr_b16 v[120:121], v192 offset:49152
	ds_read_b64_tr_b16 v[122:123], v192 offset:49408
	s_waitcnt lgkmcnt(8)
	v_mfma_f32_32x32x16_bf16 v[176:191], v[124:127], v[128:131], v[176:191]
	ds_read_b64_tr_b16 v[124:125], v198 offset:30464
	ds_read_b64_tr_b16 v[126:127], v198 offset:31552
	ds_read_b64_tr_b16 v[128:129], v192 offset:50176
	ds_read_b64_tr_b16 v[130:131], v192 offset:50432
	s_waitcnt lgkmcnt(8)
	v_mfma_f32_32x32x16_bf16 v[176:191], v[132:135], v[136:139], v[176:191]
	s_waitcnt lgkmcnt(4)
	v_mfma_f32_32x32x16_bf16 v[176:191], v[116:119], v[120:123], v[176:191]
	s_waitcnt lgkmcnt(0)
	v_mfma_f32_32x32x16_bf16 v[176:191], v[124:127], v[128:131], v[176:191]
	s_nop 7
	s_nop 3
	v_cvt_pk_bf16_f32 v140, v176, v177
	v_cvt_pk_bf16_f32 v141, v178, v179
	v_cvt_pk_bf16_f32 v142, v180, v181
	v_cvt_pk_bf16_f32 v143, v182, v183
	v_cvt_pk_bf16_f32 v144, v184, v185
	v_cvt_pk_bf16_f32 v145, v186, v187
	v_cvt_pk_bf16_f32 v146, v188, v189
	v_cvt_pk_bf16_f32 v147, v190, v191
	ds_write_b64 v194, v[140:141] offset:0
	ds_write_b64 v194, v[142:143] offset:16
	ds_write_b64 v194, v[144:145] offset:32
	ds_write_b64 v194, v[146:147] offset:48
	s_waitcnt vmcnt(10)
	v_add_u32_e32 v154, s16, v172
	v_add_u32_e32 v155, s16, v173
	ds_read_b32 v116, v155
	ds_read_b32 v117, v154
	ds_read_b32 v118, v154 offset:512
	ds_read_b32 v152, v154 offset:256
	ds_read_b32 v153, v154 offset:768
	ds_write_b128 v170, v[4:7] offset:0
	ds_write_b128 v170, v[8:11] offset:272
	ds_write_b128 v170, v[12:15] offset:544
	ds_write_b128 v170, v[16:19] offset:816
	ds_write_b128 v170, v[20:23] offset:1088
	ds_write_b128 v170, v[24:27] offset:1360
	ds_write_b128 v170, v[28:31] offset:1632
	ds_write_b128 v170, v[32:35] offset:1904
	v_lshlrev_b32_e32 v120, 16, v36
	v_and_b32_e32 v121, 0xffff0000, v36
	v_lshlrev_b32_e32 v122, 16, v37
	v_and_b32_e32 v123, 0xffff0000, v37
	v_lshlrev_b32_e32 v124, 16, v38
	v_and_b32_e32 v125, 0xffff0000, v38
	v_lshlrev_b32_e32 v126, 16, v39
	v_and_b32_e32 v127, 0xffff0000, v39
	s_waitcnt lgkmcnt(8)
	v_sub_f32_e32 v119, v116, v117
	v_exp_f32_e32 v119, v119
	v_mul_f32_e32 v128, v118, v120
	v_mul_f32_e32 v129, v118, v121
	v_mul_f32_e32 v130, v118, v122
	v_mul_f32_e32 v131, v118, v123
	v_mul_f32_e32 v132, v118, v124
	v_mul_f32_e32 v133, v118, v125
	v_mul_f32_e32 v134, v118, v126
	v_mul_f32_e32 v135, v118, v127
	v_mul_f32_e32 v119, v118, v119
	v_cvt_pk_bf16_f32 v144, v128, v129
	v_cvt_pk_bf16_f32 v145, v130, v131
	v_cvt_pk_bf16_f32 v146, v132, v133
	v_cvt_pk_bf16_f32 v147, v134, v135
	v_mul_f32_e32 v136, v119, v120
	v_mul_f32_e32 v137, v119, v121
	v_mul_f32_e32 v138, v119, v122
	v_mul_f32_e32 v139, v119, v123
	v_mul_f32_e32 v140, v119, v124
	v_mul_f32_e32 v141, v119, v125
	v_mul_f32_e32 v142, v119, v126
	v_mul_f32_e32 v143, v119, v127
	v_cvt_pk_bf16_f32 v148, v136, v137
	v_cvt_pk_bf16_f32 v149, v138, v139
	v_cvt_pk_bf16_f32 v150, v140, v141
	v_cvt_pk_bf16_f32 v151, v142, v143
	ds_write_b128 v171, v[144:147] offset:0
	ds_write_b128 v197, v[148:151] offset:0
	v_lshlrev_b32_e32 v120, 16, v40
	v_and_b32_e32 v121, 0xffff0000, v40
	v_lshlrev_b32_e32 v122, 16, v41
	v_and_b32_e32 v123, 0xffff0000, v41
	v_lshlrev_b32_e32 v124, 16, v42
	v_and_b32_e32 v125, 0xffff0000, v42
	v_lshlrev_b32_e32 v126, 16, v43
	v_and_b32_e32 v127, 0xffff0000, v43
	v_sub_f32_e32 v119, v116, v152
	v_exp_f32_e32 v119, v119
	v_mul_f32_e32 v128, v153, v120
	v_mul_f32_e32 v129, v153, v121
	v_mul_f32_e32 v130, v153, v122
	v_mul_f32_e32 v131, v153, v123
	v_mul_f32_e32 v132, v153, v124
	v_mul_f32_e32 v133, v153, v125
	v_mul_f32_e32 v134, v153, v126
	v_mul_f32_e32 v135, v153, v127
	v_mul_f32_e32 v119, v153, v119
	v_cvt_pk_bf16_f32 v144, v128, v129
	v_cvt_pk_bf16_f32 v145, v130, v131
	v_cvt_pk_bf16_f32 v146, v132, v133
	v_cvt_pk_bf16_f32 v147, v134, v135
	v_mul_f32_e32 v136, v119, v120
	v_mul_f32_e32 v137, v119, v121
	v_mul_f32_e32 v138, v119, v122
	v_mul_f32_e32 v139, v119, v123
	v_mul_f32_e32 v140, v119, v124
	v_mul_f32_e32 v141, v119, v125
	v_mul_f32_e32 v142, v119, v126
	v_mul_f32_e32 v143, v119, v127
	v_cvt_pk_bf16_f32 v148, v136, v137
	v_cvt_pk_bf16_f32 v149, v138, v139
	v_cvt_pk_bf16_f32 v150, v140, v141
	v_cvt_pk_bf16_f32 v151, v142, v143
	ds_write_b128 v171, v[144:147] offset:4096
	ds_write_b128 v197, v[148:151] offset:4096
.Lm_nox_35:
	global_load_dwordx4 v[4:7], v164, s[38:39] offset:0
	global_load_dwordx4 v[8:11], v164, s[38:39] offset:512
	global_load_dwordx4 v[12:15], v164, s[38:39] offset:1024
	global_load_dwordx4 v[16:19], v164, s[38:39] offset:1536
	global_load_dwordx4 v[20:23], v164, s[38:39] offset:2048
	global_load_dwordx4 v[24:27], v164, s[38:39] offset:2560
	global_load_dwordx4 v[28:31], v164, s[38:39] offset:3072
	global_load_dwordx4 v[32:35], v164, s[38:39] offset:3584
	global_load_dwordx4 v[36:39], v168, s[40:41]
	global_load_dwordx4 v[40:43], v169, s[40:41]
	s_add_u32 s38, s38, s46
	s_addc_u32 s39, s39, s55
	s_add_u32 s40, s40, s47
	s_addc_u32 s41, s41, s55
.Lm_stepdone_26:
	s_waitcnt lgkmcnt(0)
	s_barrier
	s_mov_b32 s14, s16
	s_mov_b32 s16, s17
	s_add_u32 s17, s17, 1280
	s_cmpk_eq_u32 s17, 5120
	s_cselect_b32 s17, 0, s17
	s_add_u32 s50, s50, 1
	s_cmp_lt_u32 s50, 64
	s_cbranch_scc1 .Lm_loop
	s_cmp_lt_u32 s3, 4
	s_cbranch_scc0 .Lm_noflush_36
	s_nop 7
	s_nop 3
	v_fma_f32 v76, v92, v3, v76
	v_fma_f32 v77, v93, v3, v77
	v_fma_f32 v78, v94, v3, v78
	v_fma_f32 v79, v95, v3, v79
	v_fma_f32 v80, v96, v3, v80
	v_fma_f32 v81, v97, v3, v81
	v_fma_f32 v82, v98, v3, v82
	v_fma_f32 v83, v99, v3, v83
	v_fma_f32 v84, v100, v3, v84
	v_fma_f32 v85, v101, v3, v85
	v_fma_f32 v86, v102, v3, v86
	v_fma_f32 v87, v103, v3, v87
	v_fma_f32 v88, v104, v3, v88
	v_fma_f32 v89, v105, v3, v89
	v_fma_f32 v90, v106, v3, v90
	v_fma_f32 v91, v107, v3, v91
	v_cvt_pk_bf16_f32 v36, v76, v77
	v_cvt_pk_bf16_f32 v37, v78, v79
	v_cvt_pk_bf16_f32 v38, v80, v81
	v_cvt_pk_bf16_f32 v39, v82, v83
	v_cvt_pk_bf16_f32 v72, v84, v85
	v_cvt_pk_bf16_f32 v73, v86, v87
	v_cvt_pk_bf16_f32 v74, v88, v89
	v_cvt_pk_bf16_f32 v75, v90, v91
	ds_write_b64 v168, v[36:37] offset:0
	ds_write_b64 v168, v[38:39] offset:16
	ds_write_b64 v168, v[72:73] offset:32
	ds_write_b64 v168, v[74:75] offset:48
	s_waitcnt lgkmcnt(0)
	ds_read_b128 v[92:95], v169
	ds_read_b128 v[96:99], v169 offset:1280
	s_waitcnt lgkmcnt(0)
	global_store_dwordx4 v170, v[92:95], s[44:45]
	global_store_dwordx4 v171, v[96:99], s[44:45]

.LBB0_327:
	s_andn2_b64 vcc, exec, s[4:5]
	s_cbranch_vccnz .LBB0_800
	s_cmp_lt_i32 s96, 1
	s_mov_b64 s[4:5], -1
	s_cbranch_scc1 .LBB0_384
	s_cmp_eq_u32 s96, 1
	s_cbranch_scc0 .LBB0_383
	v_readlane_b32 s4, v253, 18
	v_mov_b32_e32 v1, v175
	v_readlane_b32 s5, v253, 19
	s_andn2_b64 vcc, exec, s[4:5]
	v_readfirstlane_b32 s3, v1
	s_cbranch_vccnz .LBB0_383
	v_writelane_b32 v255, s96, 7
	v_writelane_b32 v255, s97, 8
	v_writelane_b32 v255, s98, 9
	v_writelane_b32 v255, s99, 10
	v_writelane_b32 v255, s86, 0
	v_writelane_b32 v255, s87, 1
	v_writelane_b32 v255, s42, 11
	s_mov_b32 s5, 0
	v_lshrrev_b32_e32 v212, 6, v175
	s_lshl_b32 s4, s42, 8
	v_writelane_b32 v255, s5, 12
	v_readfirstlane_b32 s3, v212
	v_readlane_b32 s48, v254, 20
	v_readlane_b32 s49, v254, 21
	v_readlane_b32 s46, v254, 22
	v_readlane_b32 s47, v254, 23
	v_readlane_b32 s50, v254, 12
	v_readlane_b32 s51, v254, 13
	v_readlane_b32 s59, v253, 3
	s_mov_b32 s52, s31
	s_nop 3
	s_add_u32 s48, s48, s4
	s_addc_u32 s49, s49, 0
	s_add_u32 s46, s46, s4
	s_addc_u32 s47, s47, 0
	s_lshr_b32 s4, s4, 2
	s_add_u32 s50, s50, s4
	s_addc_u32 s51, s51, 0
	s_add_u32 s42, s36, 0x180000
	s_addc_u32 s43, s37, 0
	s_lshr_b32 s71, s3, 1
	s_and_b32 s70, s3, 1
	s_lshl_b32 s70, s70, 6
	s_movk_i32 s60, 0xc00
	v_and_b32_e32 v1, 31, v175
	v_bfe_u32 v2, v175, 5, 1
	v_lshlrev_b32_e32 v3, 2, v2
	v_sub_u32_e32 v15, v1, v3
	v_cmp_eq_u32_e64 s[66:67], 1, v2
	v_and_b32_e32 v212, 7, v175
	v_cmp_gt_u32_e64 s[62:63], 2, v212
	v_cmp_eq_u32_e64 s[64:65], 0, v212
	v_lshlrev_b32_e32 v4, 4, v212
	v_lshrrev_b32_e32 v172, 3, v175
	v_mov_b32_e32 v216, 0x90
	v_mad_u32_u24 v5, v172, v216, v4
	v_add_u32_e32 v7, 0xffffff80, v172
	v_lshlrev_b32_e32 v172, 4, v2
	v_mad_u32_u24 v8, v1, v216, v172
	v_bfe_u32 v172, v175, 2, 2
	v_add_u32_e32 v172, v172, v3
	v_bfe_u32 v217, v175, 4, 1
	v_lshlrev_b32_e32 v217, 5, v217
	v_and_b32_e32 v250, 3, v175
	v_lshl_add_u32 v217, v250, 3, v217
	v_mad_u32_u24 v9, v172, v216, v217
	v_add_u32_e32 v9, 0xd800, v9
	v_add_u32_e32 v212, s70, v1
	s_lshl_b32 s4, s71, 7
	v_lshlrev_b32_e32 v172, 4, v2
	v_add_u32_e32 v172, s4, v172
	v_mul_u32_u24_e32 v216, 0xc00, v212
	v_add_u32_e32 v10, v216, v172
	v_add_u32_e32 v11, 0x18000, v10
	v_lshlrev_b32_e32 v12, 6, v212
	s_mul_i32 s5, s3, 0x1200
	s_add_u32 s5, s5, 0x1b000
	v_mov_b32_e32 v216, 0x90
	v_lshlrev_b32_e32 v172, 3, v2
	v_mad_u32_u24 v13, v1, v216, v172
	v_add_u32_e32 v13, s5, v13
	v_and_b32_e32 v172, 63, v175
	v_lshrrev_b32_e32 v217, 3, v172
	v_and_b32_e32 v172, 7, v172
	v_lshlrev_b32_e32 v172, 4, v172
	v_mad_u32_u24 v14, v217, v216, v172
	v_add_u32_e32 v14, s5, v14
	v_add_u32_e32 v217, s70, v217
	v_lshl_add_u32 v6, v217, 11, v172
	v_add_u32_e32 v6, s4, v6
	s_cmpk_lt_i32 s52, 0x100
	s_cbranch_scc0 .Lat_exit

.Lat_output:
	s_nop 7
	s_nop 7
	v_mov_b32_e32 v212, v209
	v_mov_b32_e32 v172, v209
	s_nop 1
	v_permlane32_swap_b32_e32 v212, v172
	v_add_f32_e32 v172, v212, v172
	v_rcp_f32_e32 v172, v172
	s_nop 0
	v_mul_f32_e32 v16, v16, v172
	v_mul_f32_e32 v17, v17, v172
	v_mul_f32_e32 v18, v18, v172
	v_mul_f32_e32 v19, v19, v172
	v_mul_f32_e32 v20, v20, v172
	v_mul_f32_e32 v21, v21, v172
	v_mul_f32_e32 v22, v22, v172
	v_mul_f32_e32 v23, v23, v172
	v_mul_f32_e32 v24, v24, v172
	v_mul_f32_e32 v25, v25, v172
	v_mul_f32_e32 v26, v26, v172
	v_mul_f32_e32 v27, v27, v172
	v_mul_f32_e32 v28, v28, v172
	v_mul_f32_e32 v29, v29, v172
	v_mul_f32_e32 v30, v30, v172
	v_mul_f32_e32 v31, v31, v172
	v_mul_f32_e32 v32, v32, v172
	v_mul_f32_e32 v33, v33, v172
	v_mul_f32_e32 v34, v34, v172
	v_mul_f32_e32 v35, v35, v172
	v_mul_f32_e32 v36, v36, v172
	v_mul_f32_e32 v37, v37, v172
	v_mul_f32_e32 v38, v38, v172
	v_mul_f32_e32 v39, v39, v172
	v_mul_f32_e32 v40, v40, v172
	v_mul_f32_e32 v41, v41, v172
	v_mul_f32_e32 v42, v42, v172
	v_mul_f32_e32 v43, v43, v172
	v_mul_f32_e32 v44, v44, v172
	v_mul_f32_e32 v45, v45, v172
	v_mul_f32_e32 v46, v46, v172
	v_mul_f32_e32 v47, v47, v172
	v_cvt_pk_bf16_f32 v164, v16, v17
	v_cvt_pk_bf16_f32 v165, v18, v19
	v_cvt_pk_bf16_f32 v166, v20, v21
	v_cvt_pk_bf16_f32 v167, v22, v23
	v_cvt_pk_bf16_f32 v168, v24, v25
	v_cvt_pk_bf16_f32 v169, v26, v27
	v_cvt_pk_bf16_f32 v170, v28, v29
	v_cvt_pk_bf16_f32 v171, v30, v31
	ds_write_b64 v13, v[164:165] offset:0
	ds_write_b64 v13, v[166:167] offset:16
	ds_write_b64 v13, v[168:169] offset:32
	ds_write_b64 v13, v[170:171] offset:48
	v_cvt_pk_bf16_f32 v164, v32, v33
	v_cvt_pk_bf16_f32 v165, v34, v35
	v_cvt_pk_bf16_f32 v166, v36, v37
	v_cvt_pk_bf16_f32 v167, v38, v39
	v_cvt_pk_bf16_f32 v168, v40, v41
	v_cvt_pk_bf16_f32 v169, v42, v43
	v_cvt_pk_bf16_f32 v170, v44, v45
	v_cvt_pk_bf16_f32 v171, v46, v47
	ds_write_b64 v13, v[164:165] offset:64
	ds_write_b64 v13, v[166:167] offset:80
	ds_write_b64 v13, v[168:169] offset:96
	ds_write_b64 v13, v[170:171] offset:112
	s_waitcnt lgkmcnt(0)
	ds_read_b128 v[80:83], v14 offset:0
	ds_read_b128 v[84:87], v14 offset:1152
	ds_read_b128 v[88:91], v14 offset:2304
	ds_read_b128 v[92:95], v14 offset:3456
	v_add_u32_e32 v212, 0x0, v6
	s_waitcnt lgkmcnt(3)
	global_store_dwordx4 v212, v[80:83], s[44:45]
	v_add_u32_e32 v212, 0x4000, v6
	s_waitcnt lgkmcnt(2)
	global_store_dwordx4 v212, v[84:87], s[44:45]
	v_add_u32_e32 v212, 0x8000, v6
	s_waitcnt lgkmcnt(1)
	global_store_dwordx4 v212, v[88:91], s[44:45]
	v_add_u32_e32 v212, 0xc000, v6
	s_waitcnt lgkmcnt(0)
	global_store_dwordx4 v212, v[92:95], s[44:45]
	v_mov_b32_e32 v212, v211
	v_mov_b32_e32 v172, v211
	s_nop 1
	v_permlane32_swap_b32_e32 v212, v172
	v_add_f32_e32 v172, v212, v172
	v_rcp_f32_e32 v172, v172
	s_nop 0
	v_mul_f32_e32 v48, v48, v172
	v_mul_f32_e32 v49, v49, v172
	v_mul_f32_e32 v50, v50, v172
	v_mul_f32_e32 v51, v51, v172
	v_mul_f32_e32 v52, v52, v172
	v_mul_f32_e32 v53, v53, v172
	v_mul_f32_e32 v54, v54, v172
	v_mul_f32_e32 v55, v55, v172
	v_mul_f32_e32 v56, v56, v172
	v_mul_f32_e32 v57, v57, v172
	v_mul_f32_e32 v58, v58, v172
	v_mul_f32_e32 v59, v59, v172
	v_mul_f32_e32 v60, v60, v172
	v_mul_f32_e32 v61, v61, v172
	v_mul_f32_e32 v62, v62, v172
	v_mul_f32_e32 v63, v63, v172
	v_mul_f32_e32 v64, v64, v172
	v_mul_f32_e32 v65, v65, v172
	v_mul_f32_e32 v66, v66, v172
	v_mul_f32_e32 v67, v67, v172
	v_mul_f32_e32 v68, v68, v172
	v_mul_f32_e32 v69, v69, v172
	v_mul_f32_e32 v70, v70, v172
	v_mul_f32_e32 v71, v71, v172
	v_mul_f32_e32 v72, v72, v172
	v_mul_f32_e32 v73, v73, v172
	v_mul_f32_e32 v74, v74, v172
	v_mul_f32_e32 v75, v75, v172
	v_mul_f32_e32 v76, v76, v172
	v_mul_f32_e32 v77, v77, v172
	v_mul_f32_e32 v78, v78, v172
	v_mul_f32_e32 v79, v79, v172
	v_cvt_pk_bf16_f32 v164, v48, v49
	v_cvt_pk_bf16_f32 v165, v50, v51
	v_cvt_pk_bf16_f32 v166, v52, v53
	v_cvt_pk_bf16_f32 v167, v54, v55
	v_cvt_pk_bf16_f32 v168, v56, v57
	v_cvt_pk_bf16_f32 v169, v58, v59
	v_cvt_pk_bf16_f32 v170, v60, v61
	v_cvt_pk_bf16_f32 v171, v62, v63
	ds_write_b64 v13, v[164:165] offset:0
	ds_write_b64 v13, v[166:167] offset:16
	ds_write_b64 v13, v[168:169] offset:32
	ds_write_b64 v13, v[170:171] offset:48
	v_cvt_pk_bf16_f32 v164, v64, v65
	v_cvt_pk_bf16_f32 v165, v66, v67
	v_cvt_pk_bf16_f32 v166, v68, v69
	v_cvt_pk_bf16_f32 v167, v70, v71
	v_cvt_pk_bf16_f32 v168, v72, v73
	v_cvt_pk_bf16_f32 v169, v74, v75
	v_cvt_pk_bf16_f32 v170, v76, v77
	v_cvt_pk_bf16_f32 v171, v78, v79
	ds_write_b64 v13, v[164:165] offset:64
	ds_write_b64 v13, v[166:167] offset:80
	ds_write_b64 v13, v[168:169] offset:96
	ds_write_b64 v13, v[170:171] offset:112
	s_waitcnt lgkmcnt(0)
	ds_read_b128 v[80:83], v14 offset:0
	ds_read_b128 v[84:87], v14 offset:1152
	ds_read_b128 v[88:91], v14 offset:2304
	ds_read_b128 v[92:95], v14 offset:3456
	v_add_u32_e32 v212, 0x10000, v6
	s_waitcnt lgkmcnt(3)
	global_store_dwordx4 v212, v[80:83], s[44:45]
	v_add_u32_e32 v212, 0x14000, v6
	s_waitcnt lgkmcnt(2)
	global_store_dwordx4 v212, v[84:87], s[44:45]
	v_add_u32_e32 v212, 0x18000, v6
	s_waitcnt lgkmcnt(1)
	global_store_dwordx4 v212, v[88:91], s[44:45]
	v_add_u32_e32 v212, 0x1c000, v6
	s_waitcnt lgkmcnt(0)
	global_store_dwordx4 v212, v[92:95], s[44:45]
